# P10 final-output stores marked nt (streaming; output is never re-read by the kernel)
# baseline (speedup 1.0000x reference)
; #define GAS __attribute__((address_space(1)))
; __device__ __forceinline__ void p10_final(Frame& F) {
;     ...
;         float s = 0.f;
; #pragma unroll
;         for (int j = 0; j < 16; ++j) s += (v[j].x * v[j].x + v[j].y * v[j].y) + (v[j].z * v[j].z + v[j].w * v[j].w);
;         const float r = 1.f / sqrtf(wave_sum(s) * (1.f / DM) + EPS);
;         GAS f32x4* orow = (GAS f32x4*)(F.out + (size_t)m * DM) + F.lane;
; #pragma unroll
;         for (int j = 0; j < 16; ++j) orow[64 * j] = v[j] * r * gr[64 * j];
.LBB0_1804:
	v_pk_mul_f32 v[64:65], v[6:7], v[6:7]
	v_pk_mul_f32 v[66:67], v[4:5], v[4:5]
	v_lshl_add_u64 v[116:117], v[116:117], 0, s[4:5]
	v_pk_mov_b32 v[68:69], v[66:67], v[64:65] op_sel:[1,0]
	v_mov_b32_e32 v67, v65
	v_pk_add_f32 v[64:65], v[68:69], v[66:67]
	v_pk_mul_f32 v[66:67], v[2:3], v[2:3]
	v_pk_add_f32 v[64:65], v[64:65], v[64:65] op_sel_hi:[0,1]
	v_pk_mul_f32 v[68:69], v[0:1], v[0:1]
	v_mul_f32_e32 v64, v12, v12
	v_pk_mov_b32 v[70:71], v[68:69], v[66:67] op_sel:[1,0]
	v_mov_b32_e32 v69, v67
	v_pk_add_f32 v[66:67], v[70:71], v[68:69]
	v_pk_fma_f32 v[68:69], v[12:13], v[12:13], v[64:65] op_sel_hi:[1,1,0]
	v_mul_f32_e32 v64, v14, v14
	v_pk_add_f32 v[66:67], v[66:67], v[66:67] op_sel_hi:[0,1]
	v_pk_fma_f32 v[70:71], v[14:15], v[14:15], v[64:65] op_sel_hi:[1,1,0]
	v_mul_f32_e32 v68, v16, v16
	v_mul_f32_e32 v70, v17, v17
	v_mul_f32_e32 v66, v18, v18
	v_mul_f32_e32 v64, v19, v19
	v_pk_add_f32 v[68:69], v[68:69], v[70:71]
	v_pk_add_f32 v[64:65], v[66:67], v[64:65]
	v_pk_mul_f32 v[66:67], v[10:11], v[10:11]
	v_pk_add_f32 v[64:65], v[68:69], v[64:65]
	v_pk_mul_f32 v[68:69], v[8:9], v[8:9]
	v_pk_add_f32 v[64:65], v[64:65], v[64:65] op_sel_hi:[0,1]
	v_pk_mov_b32 v[70:71], v[68:69], v[66:67] op_sel:[1,0]
	v_mov_b32_e32 v69, v67
	v_mul_f32_e32 v64, v20, v20
	v_pk_add_f32 v[66:67], v[70:71], v[68:69]
	v_pk_fma_f32 v[68:69], v[20:21], v[20:21], v[64:65] op_sel_hi:[1,1,0]
	v_mul_f32_e32 v64, v22, v22
	v_pk_add_f32 v[66:67], v[66:67], v[66:67] op_sel_hi:[0,1]
	v_pk_fma_f32 v[70:71], v[22:23], v[22:23], v[64:65] op_sel_hi:[1,1,0]
	v_mul_f32_e32 v68, v24, v24
	v_mul_f32_e32 v70, v25, v25
	v_mul_f32_e32 v66, v26, v26
	v_mul_f32_e32 v64, v27, v27
	v_pk_add_f32 v[68:69], v[68:69], v[70:71]
	v_pk_add_f32 v[64:65], v[66:67], v[64:65]
	v_pk_mul_f32 v[66:67], v[30:31], v[30:31]
	v_pk_add_f32 v[64:65], v[68:69], v[64:65]
	v_pk_mul_f32 v[68:69], v[28:29], v[28:29]
	v_pk_add_f32 v[64:65], v[64:65], v[64:65] op_sel_hi:[0,1]
	v_pk_mov_b32 v[70:71], v[68:69], v[66:67] op_sel:[1,0]
	v_mov_b32_e32 v69, v67
	v_mul_f32_e32 v64, v36, v36
	v_pk_add_f32 v[66:67], v[70:71], v[68:69]
	v_pk_fma_f32 v[68:69], v[36:37], v[36:37], v[64:65] op_sel_hi:[1,1,0]
	v_mul_f32_e32 v64, v38, v38
	v_pk_add_f32 v[66:67], v[66:67], v[66:67] op_sel_hi:[0,1]
	v_pk_fma_f32 v[70:71], v[38:39], v[38:39], v[64:65] op_sel_hi:[1,1,0]
	v_mul_f32_e32 v68, v44, v44
	v_mul_f32_e32 v70, v45, v45
	v_mul_f32_e32 v66, v46, v46
	v_mul_f32_e32 v64, v47, v47
	v_pk_add_f32 v[68:69], v[68:69], v[70:71]
	v_pk_add_f32 v[64:65], v[66:67], v[64:65]
	v_pk_mul_f32 v[66:67], v[50:51], v[50:51]
	v_pk_add_f32 v[64:65], v[68:69], v[64:65]
	v_pk_mul_f32 v[68:69], v[48:49], v[48:49]
	v_pk_add_f32 v[64:65], v[64:65], v[64:65] op_sel_hi:[0,1]
	v_pk_mov_b32 v[70:71], v[68:69], v[66:67] op_sel:[1,0]
	v_mov_b32_e32 v69, v67
	v_mul_f32_e32 v64, v56, v56
	v_pk_add_f32 v[66:67], v[70:71], v[68:69]
	v_pk_fma_f32 v[68:69], v[56:57], v[56:57], v[64:65] op_sel_hi:[1,1,0]
	v_mul_f32_e32 v64, v58, v58
	v_pk_add_f32 v[66:67], v[66:67], v[66:67] op_sel_hi:[0,1]
	v_pk_fma_f32 v[70:71], v[58:59], v[58:59], v[64:65] op_sel_hi:[1,1,0]
	v_mul_f32_e32 v68, v32, v32
	v_mul_f32_e32 v70, v33, v33
	v_mul_f32_e32 v66, v34, v34
	v_mul_f32_e32 v64, v35, v35
	v_pk_add_f32 v[68:69], v[68:69], v[70:71]
	v_pk_add_f32 v[64:65], v[66:67], v[64:65]
	v_pk_mul_f32 v[66:67], v[54:55], v[54:55]
	v_pk_add_f32 v[64:65], v[68:69], v[64:65]
	v_pk_mul_f32 v[68:69], v[52:53], v[52:53]
	v_pk_add_f32 v[64:65], v[64:65], v[64:65] op_sel_hi:[0,1]
	v_pk_mov_b32 v[70:71], v[68:69], v[66:67] op_sel:[1,0]
	v_mov_b32_e32 v69, v67
	v_mul_f32_e32 v64, v60, v60
	v_pk_add_f32 v[66:67], v[70:71], v[68:69]
	v_pk_fma_f32 v[68:69], v[60:61], v[60:61], v[64:65] op_sel_hi:[1,1,0]
	v_mul_f32_e32 v64, v62, v62
	v_pk_add_f32 v[66:67], v[66:67], v[66:67] op_sel_hi:[0,1]
	v_pk_fma_f32 v[70:71], v[62:63], v[62:63], v[64:65] op_sel_hi:[1,1,0]
	v_mul_f32_e32 v68, v40, v40
	v_mul_f32_e32 v70, v41, v41
	v_mul_f32_e32 v66, v42, v42
	v_mul_f32_e32 v64, v43, v43
	v_pk_add_f32 v[70:71], v[68:69], v[70:71]
	v_pk_add_f32 v[64:65], v[66:67], v[64:65]
	ds_read_b128 v[66:69], v230
	v_pk_add_f32 v[64:65], v[70:71], v[64:65]
	s_nop 0
	v_add_f32_e32 v64, v64, v65
	ds_bpermute_b32 v65, v144, v64
	s_waitcnt lgkmcnt(0)
	v_add_f32_e32 v64, v64, v65
	ds_bpermute_b32 v65, v145, v64
	s_waitcnt lgkmcnt(0)
	v_add_f32_e32 v64, v64, v65
	ds_bpermute_b32 v65, v146, v64
	s_waitcnt lgkmcnt(0)
	v_add_f32_e32 v64, v64, v65
	ds_bpermute_b32 v65, v147, v64
	s_waitcnt lgkmcnt(0)
	v_add_f32_e32 v64, v64, v65
	ds_bpermute_b32 v65, v148, v64
	s_waitcnt lgkmcnt(0)
	v_add_f32_e32 v64, v64, v65
	ds_bpermute_b32 v65, v149, v64
	s_waitcnt lgkmcnt(0)
	v_add_f32_e32 v64, v64, v65
	v_fmamk_f32 v64, v64, 0x39800000, v150
	v_mul_f32_e32 v65, 0x4f800000, v64
	v_cmp_gt_f32_e32 vcc, s23, v64
	s_nop 1
	v_cndmask_b32_e32 v64, v64, v65, vcc
	v_sqrt_f32_e32 v65, v64
	s_nop 0
	v_add_u32_e32 v70, -1, v65
	v_fma_f32 v71, -v70, v65, v64
	v_cmp_ge_f32_e64 s[0:1], 0, v71
	v_add_u32_e32 v71, 1, v65
	s_nop 0
	v_cndmask_b32_e64 v70, v65, v70, s[0:1]
	v_fma_f32 v65, -v71, v65, v64
	v_cmp_lt_f32_e64 s[0:1], 0, v65
	s_nop 1
	v_cndmask_b32_e64 v65, v70, v71, s[0:1]
	v_mul_f32_e32 v70, 0x37800000, v65
	v_cndmask_b32_e32 v65, v65, v70, vcc
	v_cmp_class_f32_e32 vcc, v64, v151
	s_nop 1
	v_cndmask_b32_e32 v64, v65, v64, vcc
	v_div_scale_f32 v65, s[0:1], v64, v64, 1.0
	v_rcp_f32_e32 v70, v65
	s_lshl_b64 s[0:1], s[6:7], 14
	s_add_u32 s24, s24, s94
	s_addc_u32 s25, s25, s95
	v_fma_f32 v71, -v65, v70, 1.0
	v_fmac_f32_e32 v70, v71, v70
	v_div_scale_f32 v71, vcc, 1.0, v64, 1.0
	v_mul_f32_e32 v72, v71, v70
	v_fma_f32 v73, -v65, v72, v71
	v_fmac_f32_e32 v72, v73, v70
	v_fma_f32 v65, -v65, v72, v71
	v_div_fmas_f32 v65, v65, v70, v72
	v_div_fixup_f32 v64, v65, v64, 1.0
	v_pk_mul_f32 v[4:5], v[4:5], v[64:65] op_sel_hi:[1,0]
	v_pk_mul_f32 v[6:7], v[6:7], v[64:65] op_sel_hi:[1,0]
	v_lshl_add_u64 v[70:71], v[114:115], 0, s[0:1]
	s_waitcnt lgkmcnt(0)
; #define GAS __attribute__((address_space(1)))
; __device__ __forceinline__ void p10_final(Frame& F) {
;     ...
;     for (int m = gw; m < MT; m += NGW) {
;     ...
;         GAS f32x4* orow = (GAS f32x4*)(F.out + (size_t)m * DM) + F.lane;
; #pragma unroll
;         for (int j = 0; j < 16; ++j) orow[64 * j] = v[j] * r * gr[64 * j];
	v_pk_mul_f32 v[6:7], v[68:69], v[6:7]
	v_pk_mul_f32 v[4:5], v[66:67], v[4:5]
	global_store_dwordx4 v[70:71], v[4:7], off nt
	s_nop 0
	ds_read_b128 v[4:7], v230 offset:1024
	v_pk_mul_f32 v[2:3], v[2:3], v[64:65] op_sel_hi:[1,0]
	v_pk_mul_f32 v[0:1], v[0:1], v[64:65] op_sel_hi:[1,0]
	v_pk_mul_f32 v[8:9], v[8:9], v[64:65] op_sel_hi:[1,0]
	s_cmpk_lt_i32 s24, 0x4400
	s_waitcnt lgkmcnt(0)
	v_pk_mul_f32 v[0:1], v[4:5], v[0:1]
	v_pk_mul_f32 v[2:3], v[6:7], v[2:3]
	global_store_dwordx4 v[70:71], v[0:3], off offset:1024 nt
	s_nop 0
	ds_read_b128 v[0:3], v230 offset:2048
	v_pk_mul_f32 v[4:5], v[14:15], v[64:65] op_sel_hi:[1,0]
	v_pk_mul_f32 v[6:7], v[12:13], v[64:65] op_sel_hi:[1,0]
	s_waitcnt lgkmcnt(0)
	v_pk_mul_f32 v[2:3], v[2:3], v[4:5]
	v_pk_mul_f32 v[0:1], v[0:1], v[6:7]
	global_store_dwordx4 v[70:71], v[0:3], off offset:2048 nt
	s_nop 0
	ds_read_b128 v[0:3], v230 offset:3072
	v_pk_mul_f32 v[4:5], v[18:19], v[64:65] op_sel_hi:[1,0]
	v_pk_mul_f32 v[6:7], v[16:17], v[64:65] op_sel_hi:[1,0]
	s_waitcnt lgkmcnt(0)
	v_pk_mul_f32 v[2:3], v[2:3], v[4:5]
	v_pk_mul_f32 v[0:1], v[0:1], v[6:7]
	global_store_dwordx4 v[70:71], v[0:3], off offset:3072 nt
	s_nop 0
	ds_read_b128 v[0:3], v230 offset:4096
	v_add_co_u32_e32 v4, vcc, s15, v70
	v_pk_mul_f32 v[6:7], v[10:11], v[64:65] op_sel_hi:[1,0]
	s_nop 0
	v_addc_co_u32_e32 v5, vcc, 0, v71, vcc
	v_pk_mul_f32 v[10:11], v[20:21], v[64:65] op_sel_hi:[1,0]
	s_waitcnt lgkmcnt(0)
	v_pk_mul_f32 v[0:1], v[0:1], v[8:9]
	v_pk_mul_f32 v[2:3], v[2:3], v[6:7]
	global_store_dwordx4 v[4:5], v[0:3], off offset:-4096 nt
	s_nop 0
	ds_read_b128 v[0:3], v230 offset:5120
	v_add_co_u32_e32 v6, vcc, s11, v70
	v_pk_mul_f32 v[8:9], v[22:23], v[64:65] op_sel_hi:[1,0]
	s_nop 0
	v_addc_co_u32_e32 v7, vcc, 0, v71, vcc
	s_waitcnt lgkmcnt(0)
	v_pk_mul_f32 v[0:1], v[0:1], v[10:11]
	v_pk_mul_f32 v[2:3], v[2:3], v[8:9]
	global_store_dwordx4 v[6:7], v[0:3], off offset:1024 nt
	s_nop 0
	ds_read_b128 v[0:3], v230 offset:6144
	v_pk_mul_f32 v[8:9], v[26:27], v[64:65] op_sel_hi:[1,0]
	v_pk_mul_f32 v[10:11], v[24:25], v[64:65] op_sel_hi:[1,0]
	s_waitcnt lgkmcnt(0)
	v_pk_mul_f32 v[2:3], v[2:3], v[8:9]
	v_pk_mul_f32 v[0:1], v[0:1], v[10:11]
	global_store_dwordx4 v[6:7], v[0:3], off offset:2048 nt
	s_nop 0
	ds_read_b128 v[0:3], v230 offset:7168
	v_pk_mul_f32 v[8:9], v[30:31], v[64:65] op_sel_hi:[1,0]
	v_pk_mul_f32 v[10:11], v[28:29], v[64:65] op_sel_hi:[1,0]
	s_waitcnt lgkmcnt(0)
	v_pk_mul_f32 v[2:3], v[2:3], v[8:9]
	v_pk_mul_f32 v[0:1], v[0:1], v[10:11]
	global_store_dwordx4 v[6:7], v[0:3], off offset:3072 nt
	s_nop 0
	ds_read_b128 v[0:3], v230 offset:8192
	v_pk_mul_f32 v[6:7], v[38:39], v[64:65] op_sel_hi:[1,0]
	v_pk_mul_f32 v[8:9], v[36:37], v[64:65] op_sel_hi:[1,0]
	s_waitcnt lgkmcnt(0)
	v_pk_mul_f32 v[2:3], v[2:3], v[6:7]
	v_pk_mul_f32 v[0:1], v[0:1], v[8:9]
	global_store_dwordx4 v[4:5], v[0:3], off nt
	s_nop 0
	ds_read_b128 v[0:3], v230 offset:9216
	v_pk_mul_f32 v[6:7], v[46:47], v[64:65] op_sel_hi:[1,0]
	v_pk_mul_f32 v[8:9], v[44:45], v[64:65] op_sel_hi:[1,0]
	s_waitcnt lgkmcnt(0)
	v_pk_mul_f32 v[2:3], v[2:3], v[6:7]
	v_pk_mul_f32 v[0:1], v[0:1], v[8:9]
	global_store_dwordx4 v[4:5], v[0:3], off offset:1024 nt
	s_nop 0
	ds_read_b128 v[0:3], v230 offset:10240
	v_pk_mul_f32 v[6:7], v[50:51], v[64:65] op_sel_hi:[1,0]
	v_pk_mul_f32 v[8:9], v[48:49], v[64:65] op_sel_hi:[1,0]
	s_waitcnt lgkmcnt(0)
	v_pk_mul_f32 v[2:3], v[2:3], v[6:7]
	v_pk_mul_f32 v[0:1], v[0:1], v[8:9]
	global_store_dwordx4 v[4:5], v[0:3], off offset:2048 nt
	s_nop 0
	ds_read_b128 v[0:3], v230 offset:11264
	v_pk_mul_f32 v[6:7], v[58:59], v[64:65] op_sel_hi:[1,0]
	v_pk_mul_f32 v[8:9], v[56:57], v[64:65] op_sel_hi:[1,0]
	s_waitcnt lgkmcnt(0)
	v_pk_mul_f32 v[2:3], v[2:3], v[6:7]
	v_pk_mul_f32 v[0:1], v[0:1], v[8:9]
	global_store_dwordx4 v[4:5], v[0:3], off offset:3072 nt
	s_nop 0
	ds_read_b128 v[0:3], v230 offset:12288
	v_add_co_u32_e32 v4, vcc, s19, v70
	v_pk_mul_f32 v[6:7], v[34:35], v[64:65] op_sel_hi:[1,0]
	v_pk_mul_f32 v[8:9], v[32:33], v[64:65] op_sel_hi:[1,0]
	v_addc_co_u32_e32 v5, vcc, 0, v71, vcc
	s_waitcnt lgkmcnt(0)
	v_pk_mul_f32 v[0:1], v[0:1], v[8:9]
	v_pk_mul_f32 v[2:3], v[2:3], v[6:7]
	global_store_dwordx4 v[4:5], v[0:3], off nt
	s_nop 0
	ds_read_b128 v[0:3], v230 offset:13312
	v_pk_mul_f32 v[6:7], v[54:55], v[64:65] op_sel_hi:[1,0]
	v_pk_mul_f32 v[8:9], v[52:53], v[64:65] op_sel_hi:[1,0]
	s_waitcnt lgkmcnt(0)
	v_pk_mul_f32 v[2:3], v[6:7], v[2:3]
	v_pk_mul_f32 v[0:1], v[8:9], v[0:1]
	global_store_dwordx4 v[4:5], v[0:3], off offset:1024 nt
	s_nop 0
	ds_read_b128 v[0:3], v230 offset:14336
	v_pk_mul_f32 v[6:7], v[62:63], v[64:65] op_sel_hi:[1,0]
	v_pk_mul_f32 v[8:9], v[60:61], v[64:65] op_sel_hi:[1,0]
	s_waitcnt lgkmcnt(0)
	v_pk_mul_f32 v[2:3], v[6:7], v[2:3]
	v_pk_mul_f32 v[0:1], v[8:9], v[0:1]
	global_store_dwordx4 v[4:5], v[0:3], off offset:2048 nt
	s_nop 0
	ds_read_b128 v[0:3], v230 offset:15360
	v_pk_mul_f32 v[6:7], v[42:43], v[64:65] op_sel_hi:[1,0]
	v_pk_mul_f32 v[8:9], v[40:41], v[64:65] op_sel_hi:[1,0]
	s_waitcnt lgkmcnt(0)
	v_pk_mul_f32 v[2:3], v[6:7], v[2:3]
	v_pk_mul_f32 v[0:1], v[8:9], v[0:1]
	global_store_dwordx4 v[4:5], v[0:3], off offset:3072 nt
	s_cbranch_scc0 .LBB0_1809
